# alow mini-GEMM: all 32 fragment loads issued up front into v26-v153 with counted vmcnt waits (on top of barrier edits)
# speedup vs baseline: 1.0136x; 1.0025x over previous
.LBB0_244:
	s_mul_hi_i32 s15, s14, 0x38e38e39
	s_lshr_b32 s18, s15, 31
	s_ashr_i32 s15, s15, 7
	s_add_i32 s15, s15, s18
	s_mul_i32 s18, s15, 0xffffdc00
	s_add_i32 s18, s18, s0
	v_add_u32_e32 v2, s18, v12
	v_ashrrev_i32_e32 v3, 31, v2
	v_readlane_b32 s20, v245, 9
	v_lshlrev_b64 v[2:3], 12, v[2:3]
	v_readlane_b32 s21, v245, 10
	s_add_i32 s19, s14, 0x23f
	s_nop 0
	v_lshl_add_u64 v[2:3], s[20:21], 0, v[2:3]
	s_lshl_b32 s20, s15, 9
	s_ashr_i32 s21, s20, 31
	s_lshl_b64 s[20:21], s[20:21], 1
	v_lshl_add_u64 v[2:3], v[2:3], 0, s[20:21]
	v_lshl_add_u64 v[22:23], v[2:3], 0, v[172:173]
	v_lshl_add_u64 v[24:25], v[6:7], 0, s[20:21]
	s_cmpk_gt_u32 s19, 0x47e
	global_load_dwordx4 v[26:29], v[22:23], off
	global_load_dwordx4 v[90:93], v[24:25], off
	global_load_dwordx4 v[30:33], v[22:23], off offset:64
	global_load_dwordx4 v[94:97], v[24:25], off offset:64
	global_load_dwordx4 v[34:37], v[22:23], off offset:128
	global_load_dwordx4 v[98:101], v[24:25], off offset:128
	global_load_dwordx4 v[38:41], v[22:23], off offset:192
	global_load_dwordx4 v[102:105], v[24:25], off offset:192
	global_load_dwordx4 v[42:45], v[22:23], off offset:256
	global_load_dwordx4 v[106:109], v[24:25], off offset:256
	global_load_dwordx4 v[46:49], v[22:23], off offset:320
	global_load_dwordx4 v[110:113], v[24:25], off offset:320
	global_load_dwordx4 v[50:53], v[22:23], off offset:384
	global_load_dwordx4 v[114:117], v[24:25], off offset:384
	global_load_dwordx4 v[54:57], v[22:23], off offset:448
	global_load_dwordx4 v[118:121], v[24:25], off offset:448
	global_load_dwordx4 v[58:61], v[22:23], off offset:512
	global_load_dwordx4 v[122:125], v[24:25], off offset:512
	global_load_dwordx4 v[62:65], v[22:23], off offset:576
	global_load_dwordx4 v[126:129], v[24:25], off offset:576
	global_load_dwordx4 v[66:69], v[22:23], off offset:640
	global_load_dwordx4 v[130:133], v[24:25], off offset:640
	global_load_dwordx4 v[70:73], v[22:23], off offset:704
	global_load_dwordx4 v[134:137], v[24:25], off offset:704
	global_load_dwordx4 v[74:77], v[22:23], off offset:768
	global_load_dwordx4 v[138:141], v[24:25], off offset:768
	global_load_dwordx4 v[78:81], v[22:23], off offset:832
	global_load_dwordx4 v[142:145], v[24:25], off offset:832
	global_load_dwordx4 v[82:85], v[22:23], off offset:896
	global_load_dwordx4 v[146:149], v[24:25], off offset:896
	global_load_dwordx4 v[86:89], v[22:23], off offset:960
	global_load_dwordx4 v[150:153], v[24:25], off offset:960
	s_waitcnt vmcnt(30)
	v_mfma_f32_16x16x32_bf16 v[18:21], v[26:29], v[90:93], 0
	s_waitcnt vmcnt(28)
	v_mfma_f32_16x16x32_bf16 v[18:21], v[30:33], v[94:97], v[18:21]
	s_waitcnt vmcnt(26)
	v_mfma_f32_16x16x32_bf16 v[18:21], v[34:37], v[98:101], v[18:21]
	s_waitcnt vmcnt(24)
	v_mfma_f32_16x16x32_bf16 v[18:21], v[38:41], v[102:105], v[18:21]
	s_waitcnt vmcnt(22)
	v_mfma_f32_16x16x32_bf16 v[18:21], v[42:45], v[106:109], v[18:21]
	s_waitcnt vmcnt(20)
	v_mfma_f32_16x16x32_bf16 v[18:21], v[46:49], v[110:113], v[18:21]
	s_waitcnt vmcnt(18)
	v_mfma_f32_16x16x32_bf16 v[18:21], v[50:53], v[114:117], v[18:21]
	s_waitcnt vmcnt(16)
	v_mfma_f32_16x16x32_bf16 v[18:21], v[54:57], v[118:121], v[18:21]
	s_waitcnt vmcnt(14)
	v_mfma_f32_16x16x32_bf16 v[18:21], v[58:61], v[122:125], v[18:21]
	s_waitcnt vmcnt(12)
	v_mfma_f32_16x16x32_bf16 v[18:21], v[62:65], v[126:129], v[18:21]
	s_waitcnt vmcnt(10)
	v_mfma_f32_16x16x32_bf16 v[18:21], v[66:69], v[130:133], v[18:21]
	s_waitcnt vmcnt(8)
	v_mfma_f32_16x16x32_bf16 v[18:21], v[70:73], v[134:137], v[18:21]
	s_waitcnt vmcnt(6)
	v_mfma_f32_16x16x32_bf16 v[18:21], v[74:77], v[138:141], v[18:21]
	s_waitcnt vmcnt(4)
	v_mfma_f32_16x16x32_bf16 v[18:21], v[78:81], v[142:145], v[18:21]
	s_waitcnt vmcnt(2)
	v_mfma_f32_16x16x32_bf16 v[18:21], v[82:85], v[146:149], v[18:21]
	s_waitcnt vmcnt(0)
	v_mfma_f32_16x16x32_bf16 v[2:5], v[86:89], v[150:153], v[18:21]
	v_mov_b32_e32 v14, 0
	s_nop 7
	s_cbranch_scc1 .LBB0_243
	flat_load_dword v14, v[8:9]
	s_branch .LBB0_243
